# P12 sample down GEMM split in K three ways over 48 workgroups (16/14/14 K-tiles; two partial sets handed to the epilogue workgroup)
# speedup vs baseline: 1.0057x; 1.0009x over previous
; #define PH(k) if (a.ph_lo <= (k) && (k) < a.ph_hi) { if ((k) > a.ph_lo && (k) != 6) SEAM(k);
; #define GEMM_N1024(EPI, Aoff, Woff, Mrows, Kdim, rowbase, Gn, cid, ...) do { pg8::Gemm g{(const bf16_t*)(a.ws + (Aoff)) + (size_t)(rowbase) * (Kdim), (const bf16_t*)(a.ws + (Woff)), (Mrows), 1024, (Kdim)}; \
;         pg8::StaticOrder S; S.init((Mrows), 1024, (Gn), (cid)); EPI E{__VA_ARGS__, (rowbase)}; pg8::gemm_phase<EPI, pg8::StaticOrder, false, true>(lds, g, S, E); } while (0)
; template <bool DRYR = false>
; __device__ __forceinline__ void row_pass2(const Args& a, int row_lo, int row_hi, int gw, int NGW, int lane) {
;     const bf16_t* F = (const bf16_t*)(a.ws + A_GA); const float* rss = (const float*)(a.ws + WS_RSS2); float* XO = a.out + O_Y;
;     f32x4 gp[4];
; #pragma unroll
;     for (int j = 0; j < 4; ++j) gp[j] = ((const f32x4*)a.in[I_NFPOST])[lane + 64 * j];
;     for (int r0 = row_lo + 2 * gw; r0 < row_hi; r0 += 2 * NGW) {
; __global__ void __launch_bounds__(512) fwd_kernel(Args a) {
;     ...
;     PH(12) {
;         if (G >= 32 && bx < 16) GEMM_N1024(EpiN1024<2>, A_HID, WS_WDN, MS, DFF, MP, 16, bx, (bf16_t*)(a.ws + A_GA), nullptr, (float*)(a.ws + WS_RSS2));
;         else if (G >= 32) row_pass2(a, 0, MP, gw - 128, NGW - 128, lane);
;         else { row_pass2(a, 0, MP, gw, NGW, lane); GEMM_N1024(EpiN1024<2>, A_HID, WS_WDN, MS, DFF, MP, G, bx, (bf16_t*)(a.ws + A_GA), nullptr, (float*)(a.ws + WS_RSS2)); }
.LBB0_1362:
	s_cmp_lt_i32 s58, 32
	s_cselect_b64 s[0:1], -1, 0
	s_cmp_gt_i32 s58, 31
	s_cselect_b64 s[8:9], -1, 0
	s_cmp_lt_i32 s2, 48
	s_cselect_b64 s[4:5], -1, 0
	s_and_b64 s[8:9], s[4:5], s[8:9]
	s_andn2_b64 vcc, exec, s[8:9]
	s_mov_b64 s[8:9], -1
	s_cbranch_vccz .LBB0_1420
	v_lshlrev_b32_e32 v144, 4, v176
	global_load_dwordx4 v[0:3], v144, s[12:13]
	s_waitcnt lgkmcnt(0)
	global_load_dwordx4 v[4:7], v144, s[12:13] offset:1024
	global_load_dwordx4 v[8:11], v144, s[12:13] offset:2048
	global_load_dwordx4 v[12:15], v144, s[12:13] offset:3072
	s_add_u32 s8, s54, 0x2291000
	s_addc_u32 s9, s55, 0
	s_mov_b64 s[10:11], -1
	s_and_b64 vcc, exec, s[0:1]
	s_cbranch_vccz .LBB0_1413
	s_cmpk_gt_i32 s81, 0x1fff
	s_cbranch_scc1 .LBB0_1369
	v_mov_b32_e32 v145, 0
	s_lshl_b32 s0, s81, 1
	s_waitcnt vmcnt(0)
	v_lshlrev_b32_e32 v16, 3, v176
	v_mov_b32_e32 v17, v145
	v_lshl_add_u64 v[18:19], s[54:55], 0, v[16:17]
	s_mov_b64 s[10:11], 0xbc00000
	s_ashr_i32 s1, s0, 31
	v_lshl_add_u64 v[34:35], v[18:19], 0, s[10:11]
	s_lshl_b32 s10, s58, 4
	s_lshl_b64 s[14:15], s[0:1], 12
	s_add_u32 s14, s52, s14
	s_addc_u32 s15, s53, s15
	v_lshl_add_u64 v[18:19], s[14:15], 0, v[144:145]
	s_mov_b64 s[14:15], 0x1000
	s_ashr_i32 s11, s10, 31
	v_lshl_add_u64 v[36:37], v[18:19], 0, s[14:15]
	s_lshl_b64 s[14:15], s[10:11], 12
	s_lshl_b64 s[16:17], s[0:1], 2
	s_add_u32 s20, s16, 0x2291000
	s_addc_u32 s21, s17, 0
	s_lshl_b64 s[18:19], s[0:1], 11
	v_lshl_add_u64 v[32:33], s[52:53], 0, v[144:145]
	s_lshl_b64 s[16:17], s[10:11], 2
	v_or_b32_e32 v38, s18, v16
	v_mov_b32_e32 v39, s19
	s_lshl_b64 s[18:19], s[10:11], 11
	s_mov_b32 s1, 0xbc00000
	v_mov_b32_e32 v48, 0x358637bd
	s_mov_b32 s3, 0x800000
	s_branch .LBB0_1367

; template <bool DRYR = false>
; __device__ __forceinline__ void row_pass2(const Args& a, int row_lo, int row_hi, int gw, int NGW, int lane) {
;     ...
;     for (int r0 = row_lo + 2 * gw; r0 < row_hi; r0 += 2 * NGW) {
;         f32x4 xv[2][4]; u32x2 fv[2][4]; float rs[2];
; #pragma unroll
;         for (int r = 0; r < 2; ++r) { const int row = (r0 + r < row_hi) ? r0 + r : r0; rs[r] = rss[row];
;             const f32x4* xo = (const f32x4*)(XO + (size_t)row * DM) + lane; const u32x2* fr = (const u32x2*)(F + (size_t)row * DM) + lane;
; #pragma unroll
;             for (int j = 0; j < 4; ++j) { xv[r][j] = xo[64 * j]; fv[r][j] = fr[64 * j]; } }
; __global__ void __launch_bounds__(512) fwd_kernel(Args a) {
;     ...
;         else if (G >= 32) row_pass2(a, 0, MP, gw - 128, NGW - 128, lane);
.LBB0_1413:
	s_and_b64 vcc, exec, s[10:11]
	s_cbranch_vccz .LBB0_1419
	s_lshl_b32 s0, s81, 1
	s_addk_i32 s0, 0xfd00
	s_cmpk_gt_i32 s0, 0x3fff
	s_cbranch_scc1 .LBB0_1419
	s_waitcnt vmcnt(0)
	v_mov_b32_e32 v145, 0
	v_readlane_b32 s20, v252, 1
	v_readlane_b32 s21, v252, 2
	v_readlane_b32 s14, v252, 13
	v_readlane_b32 s15, v252, 14
	v_lshlrev_b32_e32 v146, 3, v176
	v_add_u32_e32 v147, 0x1000, v144
	v_mov_b32_e32 v116, 0x358637bd
	s_lshl_b32 s1, s58, 4
	s_add_i32 s4, s1, 0xfffffd00
	s_ashr_i32 s1, s0, 31
	s_lshl_b64 s[10:11], s[0:1], 12
	global_load_dwordx4 v[84:87], v144, s[14:15]
	global_load_dwordx4 v[88:91], v144, s[14:15] offset:1024
	global_load_dwordx4 v[92:95], v144, s[14:15] offset:2048
	global_load_dwordx4 v[96:99], v144, s[14:15] offset:3072
	s_add_u32 s20, s20, s10
	s_addc_u32 s21, s21, s11
	s_add_u32 s22, s52, s10
	s_addc_u32 s23, s53, s11
	s_lshl_b64 s[10:11], s[0:1], 11
	s_add_u32 s24, s54, s10
	s_addc_u32 s25, s55, s11
	s_add_u32 s26, s24, 0xbc00000
	s_addc_u32 s27, s25, 0
	s_add_u32 s24, s24, 0xde00000
	s_addc_u32 s25, s25, 0
	s_lshl_b64 s[10:11], s[0:1], 2
	s_add_u32 s16, s54, s10
	s_addc_u32 s17, s55, s11
	s_add_u32 s18, s16, 0x2291000
	s_addc_u32 s19, s17, 0
	s_add_u32 s16, s16, 0x2280000
	s_addc_u32 s17, s17, 0
	s_lshl_b32 s98, s4, 12
	s_lshl_b32 s99, s4, 11
	s_lshl_b32 s100, s4, 2
	s_mov_b32 s3, 0x800000

; #define PG8_STAGE(bufoff, gbase, voff) do { _Pragma("unroll") for (int _i = 0; _i < 2; ++_i) \
;         __builtin_amdgcn_global_load_lds((const unsigned*)((const char*)(gbase) + (voff)[_i]), (PG8_LAS unsigned*)(lds + (bufoff) + ldsw + _i * 8192), 16, 0, 0); } while (0)
; #define PG8_WAIT_V(n) asm volatile("s_waitcnt vmcnt(" #n ")" ::: "memory")
; #define PG8_BAR __builtin_amdgcn_s_barrier()
;     __host__ __device__ bool next(int i, Unit& u) const {
;         const long L = (long)i * G + c; if (L >= nwg) return false;
;         int wgid = (int)L; { const int q = nwg / NXCD, r = nwg % NXCD, xcd = wgid % NXCD, off = wgid / NXCD; wgid = (xcd < r ? xcd * (q + 1) : r * (q + 1) + (xcd - r) * q) + off; }
;         const int nig = WGM * nN, gid = wgid / nig, fm = gid * WGM, gsz = (nM - fm) < WGM ? (nM - fm) : WGM;
;         u.pm = fm + ((wgid % nig) % gsz); u.pn = (wgid % nig) / gsz; return true;
; template <class Epi, class Sched, bool ALIGN_EPI = false, bool SP2 = false>
; __device__ __forceinline__ void gemm_phase(PG8_LAS unsigned char* lds, const Gemm g, const Sched& S, const Epi& E) {
;     ...
;     const char* cA = (const char*)g.A + (size_t)cur.pm * tstep; const char* cB = (const char*)g.Bt + (size_t)cur.pn * tstep;
;     S.a_ready(cur);
;     if constexpr (SP2) {
;         PG8_STAGE(PG8_SB(0, 0), cB, voffB); PG8_STAGE(PG8_SB(0, 1), cB + hstep, voffB); PG8_STAGE(PG8_SA(0, 0), cA, voffA); PG8_STAGE(PG8_SA(0, 1), cA + hstep, voffA);
;         if (wr == 1) PG8_BAR;
;         PG8_WAIT_V(2); PG8_BAR;
;         PG8_STAGE(PG8_SB(1, 0), cB + kstep, voffB); PG8_STAGE(PG8_SA(1, 0), cA + kstep, voffA); PG8_STAGE(PG8_SB(1, 1), cB + hstep + kstep, voffB);
.LBB0_1425:
	s_add_u32 s30, s54, 0x7b00000
	s_waitcnt vmcnt(0)
	v_lshlrev_b32_e32 v0, 4, v178
	v_and_b32_e32 v1, 32, v178
	s_addc_u32 s31, s55, 0
	v_bfe_u32 v2, v178, 2, 4
	v_bitop3_b32 v8, v0, v1, 48 bitop3:0x6c
	v_lshrrev_b32_e32 v3, 3, v178
	s_movk_i32 s0, 0x70
	v_add_u32_e32 v0, 0x2000, v0
	s_add_u32 s34, s54, 0x1d00000
	v_and_or_b32 v3, v3, s0, v2
	v_lshrrev_b32_e32 v0, 7, v0
	s_movk_i32 s0, 0xf0
	s_addc_u32 s35, s55, 0
	s_lshr_b32 s99, s2, 4
	s_lshl_b32 s99, s99, 11
	s_cmp_ge_u32 s2, 32
	s_cselect_b32 s100, 0x100, 0
	s_sub_u32 s99, s99, s100
	s_add_u32 s30, s30, s99
	s_addc_u32 s31, s31, 0
	s_add_u32 s34, s34, s99
	s_addc_u32 s35, s35, 0
	s_cmp_lt_u32 s2, 16
	s_cselect_b32 s100, 12, 10
	s_cselect_b32 s101, 13, 11
	v_and_or_b32 v0, v0, s0, v2
	s_ashr_i32 s0, s4, 3
	s_add_i32 s0, s5, s0
	s_ashr_i32 s4, s0, 31
	s_lshr_b32 s4, s4, 27
	s_add_i32 s4, s0, s4
	s_ashr_i32 s4, s4, 5
	s_lshl_b32 s8, s4, 3
	v_and_b32_e32 v9, 64, v178
	s_sub_i32 s5, 4, s8
	s_lshl_b32 s4, s4, 5
	v_or_b32_e32 v1, v8, v9
	v_mul_u32_u24_e32 v10, 0x1600, v3
	v_mul_u32_u24_e32 v11, 0x1600, v0
	s_min_u32 s9, s5, 8
	s_sub_i32 s10, s0, s4
	v_or_b32_e32 v128, v10, v1
	v_or_b32_e32 v130, v11, v1
	s_sext_i32_i8 s0, s10
	v_cvt_f32_ubyte0_e32 v1, s9
	v_cvt_f32_i32_e32 v0, s0
	v_rcp_iflag_f32_e32 v2, v1
	s_lshr_b32 s3, s29, 6
	s_ashr_i32 s0, s0, 30
	s_lshr_b32 s1, s29, 8
	v_mul_f32_e32 v2, v0, v2
	v_trunc_f32_e32 v2, v2
	v_fma_f32 v0, -v2, v1, v0
	v_cvt_i32_f32_e32 v2, v2
	s_lshl_b32 s36, s3, 10
	s_or_b32 s0, s0, 1
	v_cmp_ge_f32_e64 s[4:5], |v0|, v1
	s_and_b64 s[4:5], s[4:5], exec
	s_cselect_b32 s0, s0, 0
	v_readfirstlane_b32 s4, v2
	s_add_i32 s0, s4, s0
	s_mul_i32 s4, s0, s9
	s_sub_i32 s4, s10, s4
	s_sext_i32_i8 s4, s4
	s_add_i32 s47, s8, s4
	s_bfe_i64 s[4:5], s[0:1], 0x80000
	s_mul_hi_i32 s5, s4, 0x160000
	s_mul_i32 s4, s4, 0x160000
	s_add_u32 s24, s34, s4
	s_addc_u32 s25, s35, s5
	s_add_i32 s37, s36, 0
	s_add_i32 m0, s37, 0x10000
	s_mul_i32 s9, s47, 0x160000
	global_load_lds_dwordx4 v128, s[24:25]
	s_add_i32 m0, s37, 0x12000
	s_add_u32 s4, s24, 0xb0000
	global_load_lds_dwordx4 v130, s[24:25]
	s_addc_u32 s5, s25, 0
	s_add_i32 m0, s37, 0x14000
	s_mul_hi_i32 s8, s47, 0x160000
	global_load_lds_dwordx4 v128, s[4:5]
	s_add_i32 m0, s37, 0x16000
	s_add_u32 s22, s30, s9
	s_addc_u32 s23, s31, s8
	s_add_i32 s38, s37, 0x2000
	global_load_lds_dwordx4 v130, s[4:5]
	s_mov_b32 m0, s37
	s_add_u32 s4, s22, 0xb0000
	global_load_lds_dwordx4 v128, s[22:23]
	s_mov_b32 m0, s38
	s_addc_u32 s5, s23, 0
	s_add_i32 s39, s37, 0x4000
	global_load_lds_dwordx4 v130, s[22:23]
	s_mov_b32 m0, s39
	s_add_i32 s40, s37, 0x6000
	global_load_lds_dwordx4 v128, s[4:5]
	s_mov_b32 m0, s40
	v_mov_b32_e32 v129, 0
	global_load_lds_dwordx4 v130, s[4:5]
	v_mov_b32_e32 v131, v129
	s_mov_b32 s9, 0
	v_lshl_add_u64 v[6:7], s[24:25], 0, v[128:129]
	s_waitcnt lgkmcnt(0)
	v_lshl_add_u64 v[4:5], s[24:25], 0, v[130:131]
	v_lshl_add_u64 v[2:3], s[22:23], 0, v[128:129]
	s_cmp_lg_u32 s1, 1
	v_lshl_add_u64 v[0:1], s[22:23], 0, v[130:131]
	s_cbranch_scc1 .LBB0_1427
	s_barrier

; #define PG8_STAGE(bufoff, gbase, voff) do { _Pragma("unroll") for (int _i = 0; _i < 2; ++_i) \
;         __builtin_amdgcn_global_load_lds((const unsigned*)((const char*)(gbase) + (voff)[_i]), (PG8_LAS unsigned*)(lds + (bufoff) + ldsw + _i * 8192), 16, 0, 0); } while (0)
; #define PG8_LDA(dst, b, h) do { _Pragma("unroll") for (int m = 0; m < 4; ++m) _Pragma("unroll") for (int k = 0; k < 2; ++k) dst[m][k] = *(const PG8_LAS bf16x8*)(lds + PG8_SA(b, h) + aoff + m * 2048 + k * 1024); } while (0)
; #define PG8_LDB(dst, b, h) do { _Pragma("unroll") for (int n = 0; n < 2; ++n) _Pragma("unroll") for (int k = 0; k < 2; ++k) dst[n][k] = *(const PG8_LAS bf16x8*)(lds + PG8_SB(b, h) + boff + n * 2048 + k * 1024); } while (0)
; #define PG8_WAIT_V(n) asm volatile("s_waitcnt vmcnt(" #n ")" ::: "memory")
; #define PG8_WAIT_L(n) asm volatile("s_waitcnt lgkmcnt(" #n ")" ::: "memory")
; #define PG8_BAR __builtin_amdgcn_s_barrier()
; #define PG8_SCHED __builtin_amdgcn_sched_barrier(0)
; template <class Epi, class Sched, bool ALIGN_EPI = false, bool SP2 = false>
; __device__ __forceinline__ void gemm_phase(PG8_LAS unsigned char* lds, const Gemm g, const Sched& S, const Epi& E) {
;     ...
;         const bool has_next = S.next(ui + 1, nxt);
;         const char* nA = has_next ? (const char*)g.A + (size_t)nxt.pm * tstep : cA; const char* nB = has_next ? (const char*)g.Bt + (size_t)nxt.pn * tstep : cB;
;         for (int t = 0; t < nt; t += 2) {
;             const bool last = (t == nt - 2);
;             const char* a1 = cA + (size_t)(t + 1) * kstep;
;             const char* a2 = last ? nA : cA + (size_t)(t + 2) * kstep; const char* b2 = last ? nB : cB + (size_t)(t + 2) * kstep;
;             const char* a3 = a2 + kstep; const char* b3 = b2 + kstep;
;             if (last && has_next) S.a_ready(nxt);
;             if constexpr (SP2) {
;             PG8_LDB(B0, 0, 0); PG8_LDB(B1, 0, 1); PG8_SCHED; PG8_LDA(At, 0, 0); PG8_STAGE(PG8_SA(1, 1), a1 + hstep, voffA);
;             PG8_WAIT_V(8); PG8_WAIT_L(0); PG8_BAR; PG8_MMA(0, 0, At, B0); PG8_MMA(0, 1, At, B1); PG8_BAR; PG8_SCHED;
;             PG8_LDA(At, 0, 1); PG8_STAGE(PG8_SB(0, 0), b2, voffB); PG8_STAGE(PG8_SB(0, 1), b2 + hstep, voffB); PG8_STAGE(PG8_SA(0, 0), a2, voffA);
;             PG8_WAIT_V(8); PG8_WAIT_L(0); PG8_BAR; PG8_MMA(1, 0, At, B0); PG8_MMA(1, 1, At, B1); PG8_BAR; PG8_SCHED;
.LBB0_1440:
	ds_read_b128 v[136:139], v143
	ds_read_b128 v[148:151], v143 offset:1024
	ds_read_b128 v[152:155], v143 offset:2048
	ds_read_b128 v[156:159], v143 offset:3072
	ds_read_b128 v[160:163], v144
	ds_read_b128 v[164:167], v144 offset:1024
	ds_read_b128 v[168:171], v144 offset:2048
	ds_read_b128 v[172:175], v144 offset:3072
	s_add_u32 s3, s22, 0xfff50080
	s_addc_u32 s24, s23, -1
	s_cmp_eq_u32 s51, s100
	s_cselect_b32 s27, s21, s24
	s_cselect_b32 s26, s20, s3
	s_cselect_b32 s25, s5, s50
	s_cselect_b32 s24, s4, s49
	v_lshl_add_u64 v[212:213], s[22:23], 0, v[132:133]
	s_add_i32 m0, s37, 0xc000
	ds_read_b128 v[180:183], v145
	ds_read_b128 v[184:187], v145 offset:1024
	ds_read_b128 v[188:191], v145 offset:2048
	ds_read_b128 v[192:195], v145 offset:3072
	ds_read_b128 v[196:199], v145 offset:4096
	ds_read_b128 v[200:203], v145 offset:5120
	ds_read_b128 v[204:207], v145 offset:6144
	ds_read_b128 v[208:211], v145 offset:7168
	global_load_lds_dwordx4 v[212:213], off
	v_lshl_add_u64 v[212:213], s[22:23], 0, v[134:135]
	s_add_i32 m0, s37, 0xe000
	s_nop 0
	global_load_lds_dwordx4 v[212:213], off
	s_waitcnt vmcnt(8)
	s_waitcnt lgkmcnt(0)
	s_barrier
	s_setprio 1
	s_waitcnt lgkmcnt(0)
	v_mfma_f32_16x16x32_bf16 v[124:127], v[136:139], v[180:183], v[124:127]
	v_mfma_f32_16x16x32_bf16 v[120:123], v[152:155], v[180:183], v[120:123]
	v_mfma_f32_16x16x32_bf16 v[112:115], v[136:139], v[188:191], v[112:115]
	v_mfma_f32_16x16x32_bf16 v[104:107], v[152:155], v[188:191], v[104:107]
	v_mfma_f32_16x16x32_bf16 v[96:99], v[136:139], v[196:199], v[96:99]
	v_mfma_f32_16x16x32_bf16 v[88:91], v[152:155], v[196:199], v[88:91]
	v_mfma_f32_16x16x32_bf16 v[80:83], v[136:139], v[204:207], v[80:83]
	v_mfma_f32_16x16x32_bf16 v[72:75], v[152:155], v[204:207], v[72:75]
	v_mfma_f32_16x16x32_bf16 v[124:127], v[148:151], v[184:187], v[124:127]
	v_mfma_f32_16x16x32_bf16 v[120:123], v[156:159], v[184:187], v[120:123]
	v_mfma_f32_16x16x32_bf16 v[112:115], v[148:151], v[192:195], v[112:115]
	v_mfma_f32_16x16x32_bf16 v[104:107], v[156:159], v[192:195], v[104:107]
	v_mfma_f32_16x16x32_bf16 v[96:99], v[148:151], v[200:203], v[96:99]
	v_mfma_f32_16x16x32_bf16 v[88:91], v[156:159], v[200:203], v[88:91]
	v_mfma_f32_16x16x32_bf16 v[80:83], v[148:151], v[208:211], v[80:83]
	v_mfma_f32_16x16x32_bf16 v[72:75], v[156:159], v[208:211], v[72:75]
	s_setprio 0
	s_setprio 1
	v_mfma_f32_16x16x32_bf16 v[116:119], v[160:163], v[180:183], v[116:119]
	v_mfma_f32_16x16x32_bf16 v[108:111], v[168:171], v[180:183], v[108:111]
	v_mfma_f32_16x16x32_bf16 v[100:103], v[160:163], v[188:191], v[100:103]
	v_mfma_f32_16x16x32_bf16 v[92:95], v[168:171], v[188:191], v[92:95]
	v_mfma_f32_16x16x32_bf16 v[84:87], v[160:163], v[196:199], v[84:87]
	v_mfma_f32_16x16x32_bf16 v[76:79], v[168:171], v[196:199], v[76:79]
	v_mfma_f32_16x16x32_bf16 v[68:71], v[160:163], v[204:207], v[68:71]
	v_mfma_f32_16x16x32_bf16 v[64:67], v[168:171], v[204:207], v[64:67]
	v_mfma_f32_16x16x32_bf16 v[116:119], v[164:167], v[184:187], v[116:119]
	v_mfma_f32_16x16x32_bf16 v[108:111], v[172:175], v[184:187], v[108:111]
	v_mfma_f32_16x16x32_bf16 v[100:103], v[164:167], v[192:195], v[100:103]
	v_mfma_f32_16x16x32_bf16 v[92:95], v[172:175], v[192:195], v[92:95]
	v_mfma_f32_16x16x32_bf16 v[84:87], v[164:167], v[200:203], v[84:87]
	v_mfma_f32_16x16x32_bf16 v[76:79], v[172:175], v[200:203], v[76:79]
	v_mfma_f32_16x16x32_bf16 v[68:71], v[164:167], v[208:211], v[68:71]
	v_mfma_f32_16x16x32_bf16 v[64:67], v[172:175], v[208:211], v[64:67]
	s_setprio 0
	s_barrier
	s_add_i32 s3, s43, s36
	v_lshl_add_u64 v[212:213], s[24:25], 0, v[128:129]
	s_mov_b32 m0, s3
	ds_read_b128 v[180:183], v145 offset:16384
	ds_read_b128 v[184:187], v145 offset:17408
	ds_read_b128 v[188:191], v145 offset:18432
	ds_read_b128 v[192:195], v145 offset:19456
	ds_read_b128 v[196:199], v145 offset:20480
	ds_read_b128 v[200:203], v145 offset:21504
	ds_read_b128 v[204:207], v145 offset:22528
	ds_read_b128 v[208:211], v145 offset:23552
	global_load_lds_dwordx4 v[212:213], off
	s_add_i32 m0, s3, 0x2000
	s_add_u32 s60, s24, 0xb0000
	v_lshl_add_u64 v[214:215], s[24:25], 0, v[130:131]
	s_addc_u32 s61, s25, 0
	s_add_i32 s3, s44, s36
	global_load_lds_dwordx4 v[214:215], off
	v_lshl_add_u64 v[216:217], s[60:61], 0, v[128:129]
	s_mov_b32 m0, s3
	v_lshl_add_u64 v[218:219], s[26:27], 0, v[130:131]
	global_load_lds_dwordx4 v[216:217], off
	v_lshl_add_u64 v[216:217], s[60:61], 0, v[130:131]
	s_add_i32 m0, s3, 0x2000
	s_nop 0
	global_load_lds_dwordx4 v[216:217], off
	v_lshl_add_u64 v[216:217], s[26:27], 0, v[128:129]
	s_mov_b32 m0, s37
	s_nop 0
	global_load_lds_dwordx4 v[216:217], off
	s_mov_b32 m0, s38
	s_nop 0
	global_load_lds_dwordx4 v[218:219], off
	s_waitcnt vmcnt(8)
	s_waitcnt lgkmcnt(0)
	s_barrier
; #define PG8_STAGE(bufoff, gbase, voff) do { _Pragma("unroll") for (int _i = 0; _i < 2; ++_i) \
;         __builtin_amdgcn_global_load_lds((const unsigned*)((const char*)(gbase) + (voff)[_i]), (PG8_LAS unsigned*)(lds + (bufoff) + ldsw + _i * 8192), 16, 0, 0); } while (0)
; #define PG8_LDA(dst, b, h) do { _Pragma("unroll") for (int m = 0; m < 4; ++m) _Pragma("unroll") for (int k = 0; k < 2; ++k) dst[m][k] = *(const PG8_LAS bf16x8*)(lds + PG8_SA(b, h) + aoff + m * 2048 + k * 1024); } while (0)
; #define PG8_LDB(dst, b, h) do { _Pragma("unroll") for (int n = 0; n < 2; ++n) _Pragma("unroll") for (int k = 0; k < 2; ++k) dst[n][k] = *(const PG8_LAS bf16x8*)(lds + PG8_SB(b, h) + boff + n * 2048 + k * 1024); } while (0)
; #define PG8_MMA(ai, bj, At, Bt) do { __builtin_amdgcn_s_setprio(1); _Pragma("unroll") for (int m = 0; m < 4; ++m) _Pragma("unroll") for (int n = 0; n < 2; ++n) _Pragma("unroll") for (int k = 0; k < 2; ++k) \
;         acc[ai][bj][m][n] = __builtin_amdgcn_mfma_f32_16x16x32_bf16(Bt[n][k], At[m][k], acc[ai][bj][m][n], 0, 0, 0); __builtin_amdgcn_s_setprio(0); } while (0)
; #define PG8_WAIT_V(n) asm volatile("s_waitcnt vmcnt(" #n ")" ::: "memory")
; #define PG8_WAIT_L(n) asm volatile("s_waitcnt lgkmcnt(" #n ")" ::: "memory")
; #define PG8_BAR __builtin_amdgcn_s_barrier()
; #define PG8_SCHED __builtin_amdgcn_sched_barrier(0)
; template <class Epi, class Sched, bool ALIGN_EPI = false, bool SP2 = false>
; __device__ __forceinline__ void gemm_phase(PG8_LAS unsigned char* lds, const Gemm g, const Sched& S, const Epi& E) {
;     ...
;             PG8_WAIT_V(8); PG8_WAIT_L(0); PG8_BAR; PG8_MMA(1, 0, At, B0); PG8_MMA(1, 1, At, B1); PG8_BAR; PG8_SCHED;
;             PG8_LDB(B0, 1, 0); PG8_LDB(B1, 1, 1); PG8_SCHED; PG8_LDA(At, 1, 0); PG8_STAGE(PG8_SA(0, 1), a2 + hstep, voffA);
;             PG8_WAIT_V(8); PG8_WAIT_L(0); PG8_BAR; PG8_MMA(0, 0, At, B0); PG8_MMA(0, 1, At, B1); PG8_BAR; PG8_SCHED;
	s_setprio 1
	s_waitcnt lgkmcnt(0)
	v_mfma_f32_16x16x32_bf16 v[60:63], v[136:139], v[180:183], v[60:63]
	v_mfma_f32_16x16x32_bf16 v[56:59], v[152:155], v[180:183], v[56:59]
	v_mfma_f32_16x16x32_bf16 v[48:51], v[136:139], v[188:191], v[48:51]
	v_mfma_f32_16x16x32_bf16 v[40:43], v[152:155], v[188:191], v[40:43]
	v_mfma_f32_16x16x32_bf16 v[32:35], v[136:139], v[196:199], v[32:35]
	v_mfma_f32_16x16x32_bf16 v[24:27], v[152:155], v[196:199], v[24:27]
	v_mfma_f32_16x16x32_bf16 v[16:19], v[136:139], v[204:207], v[16:19]
	v_mfma_f32_16x16x32_bf16 v[8:11], v[152:155], v[204:207], v[8:11]
	v_mfma_f32_16x16x32_bf16 v[60:63], v[148:151], v[184:187], v[60:63]
	v_mfma_f32_16x16x32_bf16 v[56:59], v[156:159], v[184:187], v[56:59]
	v_mfma_f32_16x16x32_bf16 v[48:51], v[148:151], v[192:195], v[48:51]
	v_mfma_f32_16x16x32_bf16 v[40:43], v[156:159], v[192:195], v[40:43]
	v_mfma_f32_16x16x32_bf16 v[32:35], v[148:151], v[200:203], v[32:35]
	v_mfma_f32_16x16x32_bf16 v[24:27], v[156:159], v[200:203], v[24:27]
	v_mfma_f32_16x16x32_bf16 v[16:19], v[148:151], v[208:211], v[16:19]
	v_mfma_f32_16x16x32_bf16 v[8:11], v[156:159], v[208:211], v[8:11]
	s_setprio 0
	s_setprio 1
	v_mfma_f32_16x16x32_bf16 v[52:55], v[160:163], v[180:183], v[52:55]
	v_mfma_f32_16x16x32_bf16 v[44:47], v[168:171], v[180:183], v[44:47]
	v_mfma_f32_16x16x32_bf16 v[36:39], v[160:163], v[188:191], v[36:39]
	v_mfma_f32_16x16x32_bf16 v[28:31], v[168:171], v[188:191], v[28:31]
	v_mfma_f32_16x16x32_bf16 v[20:23], v[160:163], v[196:199], v[20:23]
	v_mfma_f32_16x16x32_bf16 v[12:15], v[168:171], v[196:199], v[12:15]
	v_mfma_f32_16x16x32_bf16 v[4:7], v[160:163], v[204:207], v[4:7]
	v_mfma_f32_16x16x32_bf16 v[0:3], v[168:171], v[204:207], v[0:3]
	v_mfma_f32_16x16x32_bf16 v[52:55], v[164:167], v[184:187], v[52:55]
	v_mfma_f32_16x16x32_bf16 v[44:47], v[172:175], v[184:187], v[44:47]
	v_mfma_f32_16x16x32_bf16 v[36:39], v[164:167], v[192:195], v[36:39]
	v_mfma_f32_16x16x32_bf16 v[28:31], v[172:175], v[192:195], v[28:31]
	v_mfma_f32_16x16x32_bf16 v[20:23], v[164:167], v[200:203], v[20:23]
	v_mfma_f32_16x16x32_bf16 v[12:15], v[172:175], v[200:203], v[12:15]
	v_mfma_f32_16x16x32_bf16 v[4:7], v[164:167], v[208:211], v[4:7]
	v_mfma_f32_16x16x32_bf16 v[0:3], v[172:175], v[208:211], v[0:3]
	s_setprio 0
	s_barrier
	s_add_i32 s3, 0, 0x18000
	v_add_u32_e32 v147, s3, v141
	s_add_i32 s33, 0, 0x1c000
	ds_read_b128 v[136:139], v147
	ds_read_b128 v[148:151], v147 offset:1024
	ds_read_b128 v[152:155], v147 offset:2048
	ds_read_b128 v[156:159], v147 offset:3072
	v_add_u32_e32 v147, s33, v141
	ds_read_b128 v[160:163], v147
	ds_read_b128 v[164:167], v147 offset:1024
	ds_read_b128 v[168:171], v147 offset:2048
	ds_read_b128 v[172:175], v147 offset:3072
	s_add_u32 s26, s26, 0xb0000
	s_addc_u32 s27, s27, 0
	s_mov_b32 m0, s39
	v_lshl_add_u64 v[220:221], s[26:27], 0, v[128:129]
	ds_read_b128 v[180:183], v145 offset:32768
	ds_read_b128 v[184:187], v145 offset:33792
	ds_read_b128 v[188:191], v145 offset:34816
	ds_read_b128 v[192:195], v145 offset:35840
	ds_read_b128 v[196:199], v145 offset:36864
	ds_read_b128 v[200:203], v145 offset:37888
	ds_read_b128 v[204:207], v145 offset:38912
	ds_read_b128 v[208:211], v145 offset:39936
	global_load_lds_dwordx4 v[220:221], off
	v_lshl_add_u64 v[220:221], s[26:27], 0, v[130:131]
	s_mov_b32 m0, s40
	s_nop 0
	global_load_lds_dwordx4 v[220:221], off
	s_waitcnt vmcnt(8)
	s_waitcnt lgkmcnt(0)
	s_barrier
	s_setprio 1
	s_waitcnt lgkmcnt(0)
	v_mfma_f32_16x16x32_bf16 v[124:127], v[136:139], v[180:183], v[124:127]
	v_mfma_f32_16x16x32_bf16 v[120:123], v[152:155], v[180:183], v[120:123]
	v_mfma_f32_16x16x32_bf16 v[112:115], v[136:139], v[188:191], v[112:115]
	v_mfma_f32_16x16x32_bf16 v[104:107], v[152:155], v[188:191], v[104:107]
	v_mfma_f32_16x16x32_bf16 v[96:99], v[136:139], v[196:199], v[96:99]
	v_mfma_f32_16x16x32_bf16 v[88:91], v[152:155], v[196:199], v[88:91]
	v_mfma_f32_16x16x32_bf16 v[80:83], v[136:139], v[204:207], v[80:83]
	v_mfma_f32_16x16x32_bf16 v[72:75], v[152:155], v[204:207], v[72:75]
	v_mfma_f32_16x16x32_bf16 v[124:127], v[148:151], v[184:187], v[124:127]
	v_mfma_f32_16x16x32_bf16 v[120:123], v[156:159], v[184:187], v[120:123]
	v_mfma_f32_16x16x32_bf16 v[112:115], v[148:151], v[192:195], v[112:115]
	v_mfma_f32_16x16x32_bf16 v[104:107], v[156:159], v[192:195], v[104:107]
	v_mfma_f32_16x16x32_bf16 v[96:99], v[148:151], v[200:203], v[96:99]
	v_mfma_f32_16x16x32_bf16 v[88:91], v[156:159], v[200:203], v[88:91]
	v_mfma_f32_16x16x32_bf16 v[80:83], v[148:151], v[208:211], v[80:83]
	v_mfma_f32_16x16x32_bf16 v[72:75], v[156:159], v[208:211], v[72:75]
	s_setprio 0
	s_setprio 1
	v_mfma_f32_16x16x32_bf16 v[116:119], v[160:163], v[180:183], v[116:119]
	v_mfma_f32_16x16x32_bf16 v[108:111], v[168:171], v[180:183], v[108:111]
	v_mfma_f32_16x16x32_bf16 v[100:103], v[160:163], v[188:191], v[100:103]
	v_mfma_f32_16x16x32_bf16 v[92:95], v[168:171], v[188:191], v[92:95]
	v_mfma_f32_16x16x32_bf16 v[84:87], v[160:163], v[196:199], v[84:87]
	v_mfma_f32_16x16x32_bf16 v[76:79], v[168:171], v[196:199], v[76:79]
	v_mfma_f32_16x16x32_bf16 v[68:71], v[160:163], v[204:207], v[68:71]
	v_mfma_f32_16x16x32_bf16 v[64:67], v[168:171], v[204:207], v[64:67]
	v_mfma_f32_16x16x32_bf16 v[116:119], v[164:167], v[184:187], v[116:119]
	v_mfma_f32_16x16x32_bf16 v[108:111], v[172:175], v[184:187], v[108:111]
	v_mfma_f32_16x16x32_bf16 v[100:103], v[164:167], v[192:195], v[100:103]
	v_mfma_f32_16x16x32_bf16 v[92:95], v[172:175], v[192:195], v[92:95]
	v_mfma_f32_16x16x32_bf16 v[84:87], v[164:167], v[200:203], v[84:87]
	v_mfma_f32_16x16x32_bf16 v[76:79], v[172:175], v[200:203], v[76:79]
	v_mfma_f32_16x16x32_bf16 v[68:71], v[164:167], v[208:211], v[68:71]
	v_mfma_f32_16x16x32_bf16 v[64:67], v[172:175], v[208:211], v[64:67]
	s_setprio 0
	s_barrier
; #define PG8_STAGE(bufoff, gbase, voff) do { _Pragma("unroll") for (int _i = 0; _i < 2; ++_i) \
;         __builtin_amdgcn_global_load_lds((const unsigned*)((const char*)(gbase) + (voff)[_i]), (PG8_LAS unsigned*)(lds + (bufoff) + ldsw + _i * 8192), 16, 0, 0); } while (0)
; #define PG8_LDA(dst, b, h) do { _Pragma("unroll") for (int m = 0; m < 4; ++m) _Pragma("unroll") for (int k = 0; k < 2; ++k) dst[m][k] = *(const PG8_LAS bf16x8*)(lds + PG8_SA(b, h) + aoff + m * 2048 + k * 1024); } while (0)
; #define PG8_MMA(ai, bj, At, Bt) do { __builtin_amdgcn_s_setprio(1); _Pragma("unroll") for (int m = 0; m < 4; ++m) _Pragma("unroll") for (int n = 0; n < 2; ++n) _Pragma("unroll") for (int k = 0; k < 2; ++k) \
;         acc[ai][bj][m][n] = __builtin_amdgcn_mfma_f32_16x16x32_bf16(Bt[n][k], At[m][k], acc[ai][bj][m][n], 0, 0, 0); __builtin_amdgcn_s_setprio(0); } while (0)
; #define PG8_WAIT_V(n) asm volatile("s_waitcnt vmcnt(" #n ")" ::: "memory")
; #define PG8_WAIT_L(n) asm volatile("s_waitcnt lgkmcnt(" #n ")" ::: "memory")
; #define PG8_BAR __builtin_amdgcn_s_barrier()
; #define PG8_SCHED __builtin_amdgcn_sched_barrier(0)
; template <class Epi, class Sched, bool ALIGN_EPI = false, bool SP2 = false>
; __device__ __forceinline__ void gemm_phase(PG8_LAS unsigned char* lds, const Gemm g, const Sched& S, const Epi& E) {
;     ...
;             PG8_LDA(At, 1, 1); PG8_STAGE(PG8_SB(1, 0), b3, voffB); PG8_STAGE(PG8_SB(1, 1), b3 + hstep, voffB); PG8_STAGE(PG8_SA(1, 0), a3, voffA);
;             PG8_WAIT_V(8); PG8_WAIT_L(0); PG8_BAR; PG8_MMA(1, 0, At, B0); PG8_MMA(1, 1, At, B1); PG8_BAR; PG8_SCHED;
	s_add_i32 s3, s3, s36
	v_lshl_add_u64 v[212:213], v[212:213], 0, s[16:17]
	s_mov_b32 m0, s3
	ds_read_b128 v[180:183], v145 offset:49152
	ds_read_b128 v[184:187], v145 offset:50176
	ds_read_b128 v[188:191], v145 offset:51200
	ds_read_b128 v[192:195], v145 offset:52224
	ds_read_b128 v[196:199], v145 offset:53248
	ds_read_b128 v[200:203], v145 offset:54272
	ds_read_b128 v[204:207], v145 offset:55296
	ds_read_b128 v[208:211], v145 offset:56320
	global_load_lds_dwordx4 v[212:213], off
	s_add_i32 m0, s3, 0x2000
	s_add_u32 s24, s24, 0xb0080
	v_lshl_add_u64 v[212:213], v[214:215], 0, s[16:17]
	s_addc_u32 s25, s25, 0
	s_add_i32 s3, s33, s36
	global_load_lds_dwordx4 v[212:213], off
	v_lshl_add_u64 v[212:213], s[24:25], 0, v[128:129]
	s_mov_b32 m0, s3
	s_nop 0
	global_load_lds_dwordx4 v[212:213], off
	v_lshl_add_u64 v[212:213], s[24:25], 0, v[130:131]
	s_add_i32 m0, s3, 0x2000
	s_nop 0
	global_load_lds_dwordx4 v[212:213], off
	v_lshl_add_u64 v[212:213], v[216:217], 0, s[16:17]
	s_mov_b32 m0, s41
	s_nop 0
	global_load_lds_dwordx4 v[212:213], off
	v_lshl_add_u64 v[212:213], v[218:219], 0, s[16:17]
	s_mov_b32 m0, s42
	s_nop 0
	global_load_lds_dwordx4 v[212:213], off
	s_waitcnt vmcnt(8)
	s_waitcnt lgkmcnt(0)
	s_barrier
	s_setprio 1
	s_waitcnt lgkmcnt(0)
	v_mfma_f32_16x16x32_bf16 v[60:63], v[136:139], v[180:183], v[60:63]
	v_mfma_f32_16x16x32_bf16 v[56:59], v[152:155], v[180:183], v[56:59]
	v_mfma_f32_16x16x32_bf16 v[48:51], v[136:139], v[188:191], v[48:51]
	v_mfma_f32_16x16x32_bf16 v[40:43], v[152:155], v[188:191], v[40:43]
	v_mfma_f32_16x16x32_bf16 v[32:35], v[136:139], v[196:199], v[32:35]
	v_mfma_f32_16x16x32_bf16 v[24:27], v[152:155], v[196:199], v[24:27]
	v_mfma_f32_16x16x32_bf16 v[16:19], v[136:139], v[204:207], v[16:19]
	v_mfma_f32_16x16x32_bf16 v[8:11], v[152:155], v[204:207], v[8:11]
	v_mfma_f32_16x16x32_bf16 v[60:63], v[148:151], v[184:187], v[60:63]
	v_mfma_f32_16x16x32_bf16 v[56:59], v[156:159], v[184:187], v[56:59]
	v_mfma_f32_16x16x32_bf16 v[48:51], v[148:151], v[192:195], v[48:51]
	v_mfma_f32_16x16x32_bf16 v[40:43], v[156:159], v[192:195], v[40:43]
	v_mfma_f32_16x16x32_bf16 v[32:35], v[148:151], v[200:203], v[32:35]
	v_mfma_f32_16x16x32_bf16 v[24:27], v[156:159], v[200:203], v[24:27]
	v_mfma_f32_16x16x32_bf16 v[16:19], v[148:151], v[208:211], v[16:19]
	v_mfma_f32_16x16x32_bf16 v[8:11], v[156:159], v[208:211], v[8:11]
	s_setprio 0
	s_setprio 1
	v_mfma_f32_16x16x32_bf16 v[52:55], v[160:163], v[180:183], v[52:55]
	v_mfma_f32_16x16x32_bf16 v[44:47], v[168:171], v[180:183], v[44:47]
	v_mfma_f32_16x16x32_bf16 v[36:39], v[160:163], v[188:191], v[36:39]
	v_mfma_f32_16x16x32_bf16 v[28:31], v[168:171], v[188:191], v[28:31]
	v_mfma_f32_16x16x32_bf16 v[20:23], v[160:163], v[196:199], v[20:23]
	v_mfma_f32_16x16x32_bf16 v[12:15], v[168:171], v[196:199], v[12:15]
	v_mfma_f32_16x16x32_bf16 v[4:7], v[160:163], v[204:207], v[4:7]
	v_mfma_f32_16x16x32_bf16 v[0:3], v[168:171], v[204:207], v[0:3]
	v_mfma_f32_16x16x32_bf16 v[52:55], v[164:167], v[184:187], v[52:55]
	v_mfma_f32_16x16x32_bf16 v[44:47], v[172:175], v[184:187], v[44:47]
	v_mfma_f32_16x16x32_bf16 v[36:39], v[164:167], v[192:195], v[36:39]
	v_mfma_f32_16x16x32_bf16 v[28:31], v[172:175], v[192:195], v[28:31]
	v_mfma_f32_16x16x32_bf16 v[20:23], v[164:167], v[200:203], v[20:23]
	v_mfma_f32_16x16x32_bf16 v[12:15], v[172:175], v[200:203], v[12:15]
	v_mfma_f32_16x16x32_bf16 v[4:7], v[164:167], v[208:211], v[4:7]
	v_mfma_f32_16x16x32_bf16 v[0:3], v[172:175], v[208:211], v[0:3]
	s_setprio 0
	s_barrier
	s_add_i32 s51, s51, 2
	s_add_u32 s22, s22, 0x100
	s_addc_u32 s23, s23, 0
	s_add_u32 s49, s49, 0x100
	s_addc_u32 s50, s50, 0
	s_cmp_gt_u32 s51, s101
	s_cbranch_scc0 .LBB0_1440
; #define GEMM_N1024(EPI, Aoff, Woff, Mrows, Kdim, rowbase, Gn, cid, ...) do { pg8::Gemm g{(const bf16_t*)(a.ws + (Aoff)) + (size_t)(rowbase) * (Kdim), (const bf16_t*)(a.ws + (Woff)), (Mrows), 1024, (Kdim)}; \
;         pg8::StaticOrder S; S.init((Mrows), 1024, (Gn), (cid)); EPI E{__VA_ARGS__, (rowbase)}; pg8::gemm_phase<EPI, pg8::StaticOrder, false, true>(lds, g, S, E); } while (0)
; __global__ void __launch_bounds__(512) fwd_kernel(Args a) {
;     ...
;         if (G >= 32 && bx < 16) GEMM_N1024(EpiN1024<2>, A_HID, WS_WDN, MS, DFF, MP, 16, bx, (bf16_t*)(a.ws + A_GA), nullptr, (float*)(a.ws + WS_RSS2));
	s_and_b32 s100, s2, 15
	v_readfirstlane_b32 s101, v178
	s_lshl_b32 s98, s100, 18
	s_lshr_b32 s101, s101, 6
	s_lshl_b32 s99, s101, 15
	s_add_u32 s98, s98, s99
	s_lshl_b32 s100, s100, 2
	s_add_u32 s98, s54, s98
	s_addc_u32 s99, s55, 0
	s_add_u32 s98, s98, 0x9a00000
	s_addc_u32 s99, s99, 0
	s_cmp_ge_u32 s2, 32
	s_cselect_b32 s101, 0x400000, 0
	s_add_u32 s98, s98, s101
	s_addc_u32 s99, s99, 0
	s_add_u32 s100, s54, s100
	s_addc_u32 s101, s55, 0
	s_add_u32 s100, s100, 0x22a2000
	s_addc_u32 s101, s101, 0
	v_lshlrev_b32_e32 v160, 4, v176
	v_mov_b32_e32 v161, 0
	s_cmp_lt_u32 s2, 16
	s_cbranch_scc1 .Lsk_reader
	global_store_dwordx4 v160, v[0:3], s[98:99]
	s_add_u32 s98, s98, 0x400
	s_addc_u32 s99, s99, 0
	global_store_dwordx4 v160, v[4:7], s[98:99]
	s_add_u32 s98, s98, 0x400
	s_addc_u32 s99, s99, 0
	global_store_dwordx4 v160, v[8:11], s[98:99]
	s_add_u32 s98, s98, 0x400
	s_addc_u32 s99, s99, 0
	global_store_dwordx4 v160, v[12:15], s[98:99]
	s_add_u32 s98, s98, 0x400
	s_addc_u32 s99, s99, 0
	global_store_dwordx4 v160, v[16:19], s[98:99]
	s_add_u32 s98, s98, 0x400
	s_addc_u32 s99, s99, 0
	global_store_dwordx4 v160, v[20:23], s[98:99]
	s_add_u32 s98, s98, 0x400
	s_addc_u32 s99, s99, 0
	global_store_dwordx4 v160, v[24:27], s[98:99]
	s_add_u32 s98, s98, 0x400
	s_addc_u32 s99, s99, 0
	global_store_dwordx4 v160, v[28:31], s[98:99]
	s_add_u32 s98, s98, 0x400
	s_addc_u32 s99, s99, 0
	global_store_dwordx4 v160, v[32:35], s[98:99]
	s_add_u32 s98, s98, 0x400
	s_addc_u32 s99, s99, 0
	global_store_dwordx4 v160, v[36:39], s[98:99]
	s_add_u32 s98, s98, 0x400
	s_addc_u32 s99, s99, 0
	global_store_dwordx4 v160, v[40:43], s[98:99]
	s_add_u32 s98, s98, 0x400
	s_addc_u32 s99, s99, 0
	global_store_dwordx4 v160, v[44:47], s[98:99]
	s_add_u32 s98, s98, 0x400
	s_addc_u32 s99, s99, 0
	global_store_dwordx4 v160, v[48:51], s[98:99]
	s_add_u32 s98, s98, 0x400
	s_addc_u32 s99, s99, 0
	global_store_dwordx4 v160, v[52:55], s[98:99]
	s_add_u32 s98, s98, 0x400
	s_addc_u32 s99, s99, 0
	global_store_dwordx4 v160, v[56:59], s[98:99]
	s_add_u32 s98, s98, 0x400
	s_addc_u32 s99, s99, 0
	global_store_dwordx4 v160, v[60:63], s[98:99]
	s_add_u32 s98, s98, 0x400
	s_addc_u32 s99, s99, 0
	global_store_dwordx4 v160, v[64:67], s[98:99]
	s_add_u32 s98, s98, 0x400
	s_addc_u32 s99, s99, 0
	global_store_dwordx4 v160, v[68:71], s[98:99]
	s_add_u32 s98, s98, 0x400
	s_addc_u32 s99, s99, 0
	global_store_dwordx4 v160, v[72:75], s[98:99]
	s_add_u32 s98, s98, 0x400
	s_addc_u32 s99, s99, 0
	global_store_dwordx4 v160, v[76:79], s[98:99]
	s_add_u32 s98, s98, 0x400
	s_addc_u32 s99, s99, 0
	global_store_dwordx4 v160, v[80:83], s[98:99]
	s_add_u32 s98, s98, 0x400
	s_addc_u32 s99, s99, 0
	global_store_dwordx4 v160, v[84:87], s[98:99]
	s_add_u32 s98, s98, 0x400
	s_addc_u32 s99, s99, 0
	global_store_dwordx4 v160, v[88:91], s[98:99]
	s_add_u32 s98, s98, 0x400
	s_addc_u32 s99, s99, 0
	global_store_dwordx4 v160, v[92:95], s[98:99]
	s_add_u32 s98, s98, 0x400
	s_addc_u32 s99, s99, 0
	global_store_dwordx4 v160, v[96:99], s[98:99]
	s_add_u32 s98, s98, 0x400
	s_addc_u32 s99, s99, 0
	global_store_dwordx4 v160, v[100:103], s[98:99]
	s_add_u32 s98, s98, 0x400
	s_addc_u32 s99, s99, 0
	global_store_dwordx4 v160, v[104:107], s[98:99]
	s_add_u32 s98, s98, 0x400
	s_addc_u32 s99, s99, 0
	global_store_dwordx4 v160, v[108:111], s[98:99]
	s_add_u32 s98, s98, 0x400
	s_addc_u32 s99, s99, 0
	global_store_dwordx4 v160, v[112:115], s[98:99]
	s_add_u32 s98, s98, 0x400
	s_addc_u32 s99, s99, 0
	global_store_dwordx4 v160, v[116:119], s[98:99]
	s_add_u32 s98, s98, 0x400
	s_addc_u32 s99, s99, 0
	global_store_dwordx4 v160, v[120:123], s[98:99]
	s_add_u32 s98, s98, 0x400
	s_addc_u32 s99, s99, 0
	global_store_dwordx4 v160, v[124:127], s[98:99]
	s_add_u32 s98, s98, 0x400
	s_addc_u32 s99, s99, 0
	s_branch .LBB0_1428

; #define GEMM_N1024(EPI, Aoff, Woff, Mrows, Kdim, rowbase, Gn, cid, ...) do { pg8::Gemm g{(const bf16_t*)(a.ws + (Aoff)) + (size_t)(rowbase) * (Kdim), (const bf16_t*)(a.ws + (Woff)), (Mrows), 1024, (Kdim)}; \
;         pg8::StaticOrder S; S.init((Mrows), 1024, (Gn), (cid)); EPI E{__VA_ARGS__, (rowbase)}; pg8::gemm_phase<EPI, pg8::StaticOrder, false, true>(lds, g, S, E); } while (0)
; __global__ void __launch_bounds__(512) fwd_kernel(Args a) {
;     ...
;         if (G >= 32 && bx < 16) GEMM_N1024(EpiN1024<2>, A_HID, WS_WDN, MS, DFF, MP, 16, bx, (bf16_t*)(a.ws + A_GA), nullptr, (float*)(a.ws + WS_RSS2));
.Lsk_go:
	buffer_inv sc1
	s_waitcnt vmcnt(0)
	global_load_dwordx4 v[180:183], v160, s[98:99]
	s_add_u32 s98, s98, 0x400
	s_addc_u32 s99, s99, 0
	global_load_dwordx4 v[184:187], v160, s[98:99]
	s_add_u32 s98, s98, 0x400
	s_addc_u32 s99, s99, 0
	global_load_dwordx4 v[188:191], v160, s[98:99]
	s_add_u32 s98, s98, 0x400
	s_addc_u32 s99, s99, 0
	global_load_dwordx4 v[192:195], v160, s[98:99]
	s_add_u32 s98, s98, 0x400
	s_addc_u32 s99, s99, 0
	global_load_dwordx4 v[196:199], v160, s[98:99]
	s_add_u32 s98, s98, 0x400
	s_addc_u32 s99, s99, 0
	global_load_dwordx4 v[200:203], v160, s[98:99]
	s_add_u32 s98, s98, 0x400
	s_addc_u32 s99, s99, 0
	global_load_dwordx4 v[204:207], v160, s[98:99]
	s_add_u32 s98, s98, 0x400
	s_addc_u32 s99, s99, 0
	global_load_dwordx4 v[208:211], v160, s[98:99]
	s_add_u32 s98, s98, 0x400
	s_addc_u32 s99, s99, 0
	global_load_dwordx4 v[212:215], v160, s[98:99]
	s_add_u32 s98, s98, 0x400
	s_addc_u32 s99, s99, 0
	global_load_dwordx4 v[216:219], v160, s[98:99]
	s_add_u32 s98, s98, 0x400
	s_addc_u32 s99, s99, 0
	global_load_dwordx4 v[220:223], v160, s[98:99]
	s_add_u32 s98, s98, 0x400
	s_addc_u32 s99, s99, 0
	global_load_dwordx4 v[224:227], v160, s[98:99]
	s_add_u32 s98, s98, 0x400
	s_addc_u32 s99, s99, 0
	global_load_dwordx4 v[228:231], v160, s[98:99]
	s_add_u32 s98, s98, 0x400
	s_addc_u32 s99, s99, 0
	global_load_dwordx4 v[232:235], v160, s[98:99]
	s_add_u32 s98, s98, 0x400
	s_addc_u32 s99, s99, 0
	global_load_dwordx4 v[236:239], v160, s[98:99]
	s_add_u32 s98, s98, 0x400
	s_addc_u32 s99, s99, 0
	global_load_dwordx4 v[240:243], v160, s[98:99]
	s_add_u32 s98, s98, 0x400
	s_addc_u32 s99, s99, 0
	s_waitcnt vmcnt(8)
	v_add_f32_e32 v0, v0, v180
	v_add_f32_e32 v1, v1, v181
	v_add_f32_e32 v2, v2, v182
	v_add_f32_e32 v3, v3, v183
	v_add_f32_e32 v4, v4, v184
	v_add_f32_e32 v5, v5, v185
	v_add_f32_e32 v6, v6, v186
	v_add_f32_e32 v7, v7, v187
	v_add_f32_e32 v8, v8, v188
	v_add_f32_e32 v9, v9, v189
	v_add_f32_e32 v10, v10, v190
	v_add_f32_e32 v11, v11, v191
	v_add_f32_e32 v12, v12, v192
	v_add_f32_e32 v13, v13, v193
	v_add_f32_e32 v14, v14, v194
	v_add_f32_e32 v15, v15, v195
	v_add_f32_e32 v16, v16, v196
	v_add_f32_e32 v17, v17, v197
	v_add_f32_e32 v18, v18, v198
	v_add_f32_e32 v19, v19, v199
	v_add_f32_e32 v20, v20, v200
	v_add_f32_e32 v21, v21, v201
	v_add_f32_e32 v22, v22, v202
	v_add_f32_e32 v23, v23, v203
	v_add_f32_e32 v24, v24, v204
	v_add_f32_e32 v25, v25, v205
	v_add_f32_e32 v26, v26, v206
	v_add_f32_e32 v27, v27, v207
	v_add_f32_e32 v28, v28, v208
	v_add_f32_e32 v29, v29, v209
	v_add_f32_e32 v30, v30, v210
	v_add_f32_e32 v31, v31, v211
	global_load_dwordx4 v[180:183], v160, s[98:99]
	s_add_u32 s98, s98, 0x400
	s_addc_u32 s99, s99, 0
	global_load_dwordx4 v[184:187], v160, s[98:99]
	s_add_u32 s98, s98, 0x400
	s_addc_u32 s99, s99, 0
	global_load_dwordx4 v[188:191], v160, s[98:99]
	s_add_u32 s98, s98, 0x400
	s_addc_u32 s99, s99, 0
	global_load_dwordx4 v[192:195], v160, s[98:99]
	s_add_u32 s98, s98, 0x400
	s_addc_u32 s99, s99, 0
	global_load_dwordx4 v[196:199], v160, s[98:99]
	s_add_u32 s98, s98, 0x400
	s_addc_u32 s99, s99, 0
	global_load_dwordx4 v[200:203], v160, s[98:99]
	s_add_u32 s98, s98, 0x400
	s_addc_u32 s99, s99, 0
	global_load_dwordx4 v[204:207], v160, s[98:99]
	s_add_u32 s98, s98, 0x400
	s_addc_u32 s99, s99, 0
	global_load_dwordx4 v[208:211], v160, s[98:99]
	s_add_u32 s98, s98, 0x400
	s_addc_u32 s99, s99, 0
	s_waitcnt vmcnt(8)
	v_add_f32_e32 v32, v32, v212
	v_add_f32_e32 v33, v33, v213
	v_add_f32_e32 v34, v34, v214
	v_add_f32_e32 v35, v35, v215
	v_add_f32_e32 v36, v36, v216
	v_add_f32_e32 v37, v37, v217
	v_add_f32_e32 v38, v38, v218
	v_add_f32_e32 v39, v39, v219
	v_add_f32_e32 v40, v40, v220
	v_add_f32_e32 v41, v41, v221
	v_add_f32_e32 v42, v42, v222
	v_add_f32_e32 v43, v43, v223
	v_add_f32_e32 v44, v44, v224
	v_add_f32_e32 v45, v45, v225
	v_add_f32_e32 v46, v46, v226
	v_add_f32_e32 v47, v47, v227
	v_add_f32_e32 v48, v48, v228
	v_add_f32_e32 v49, v49, v229
	v_add_f32_e32 v50, v50, v230
	v_add_f32_e32 v51, v51, v231
	v_add_f32_e32 v52, v52, v232
	v_add_f32_e32 v53, v53, v233
	v_add_f32_e32 v54, v54, v234
	v_add_f32_e32 v55, v55, v235
	v_add_f32_e32 v56, v56, v236
	v_add_f32_e32 v57, v57, v237
	v_add_f32_e32 v58, v58, v238
	v_add_f32_e32 v59, v59, v239
	v_add_f32_e32 v60, v60, v240
	v_add_f32_e32 v61, v61, v241
	v_add_f32_e32 v62, v62, v242
	v_add_f32_e32 v63, v63, v243
	global_load_dwordx4 v[212:215], v160, s[98:99]
	s_add_u32 s98, s98, 0x400
	s_addc_u32 s99, s99, 0
	global_load_dwordx4 v[216:219], v160, s[98:99]
	s_add_u32 s98, s98, 0x400
	s_addc_u32 s99, s99, 0
	global_load_dwordx4 v[220:223], v160, s[98:99]
	s_add_u32 s98, s98, 0x400
	s_addc_u32 s99, s99, 0
	global_load_dwordx4 v[224:227], v160, s[98:99]
	s_add_u32 s98, s98, 0x400
	s_addc_u32 s99, s99, 0
	global_load_dwordx4 v[228:231], v160, s[98:99]
	s_add_u32 s98, s98, 0x400
	s_addc_u32 s99, s99, 0
	global_load_dwordx4 v[232:235], v160, s[98:99]
	s_add_u32 s98, s98, 0x400
	s_addc_u32 s99, s99, 0
	global_load_dwordx4 v[236:239], v160, s[98:99]
	s_add_u32 s98, s98, 0x400
	s_addc_u32 s99, s99, 0
	global_load_dwordx4 v[240:243], v160, s[98:99]
	s_add_u32 s98, s98, 0x400
	s_addc_u32 s99, s99, 0
	s_waitcnt vmcnt(8)
; #define GEMM_N1024(EPI, Aoff, Woff, Mrows, Kdim, rowbase, Gn, cid, ...) do { pg8::Gemm g{(const bf16_t*)(a.ws + (Aoff)) + (size_t)(rowbase) * (Kdim), (const bf16_t*)(a.ws + (Woff)), (Mrows), 1024, (Kdim)}; \
;         pg8::StaticOrder S; S.init((Mrows), 1024, (Gn), (cid)); EPI E{__VA_ARGS__, (rowbase)}; pg8::gemm_phase<EPI, pg8::StaticOrder, false, true>(lds, g, S, E); } while (0)
; __global__ void __launch_bounds__(512) fwd_kernel(Args a) {
;     ...
;         if (G >= 32 && bx < 16) GEMM_N1024(EpiN1024<2>, A_HID, WS_WDN, MS, DFF, MP, 16, bx, (bf16_t*)(a.ws + A_GA), nullptr, (float*)(a.ws + WS_RSS2));
	v_add_f32_e32 v64, v64, v180
	v_add_f32_e32 v65, v65, v181
	v_add_f32_e32 v66, v66, v182
	v_add_f32_e32 v67, v67, v183
	v_add_f32_e32 v68, v68, v184
	v_add_f32_e32 v69, v69, v185
	v_add_f32_e32 v70, v70, v186
	v_add_f32_e32 v71, v71, v187
	v_add_f32_e32 v72, v72, v188
	v_add_f32_e32 v73, v73, v189
	v_add_f32_e32 v74, v74, v190
	v_add_f32_e32 v75, v75, v191
	v_add_f32_e32 v76, v76, v192
	v_add_f32_e32 v77, v77, v193
	v_add_f32_e32 v78, v78, v194
	v_add_f32_e32 v79, v79, v195
	v_add_f32_e32 v80, v80, v196
	v_add_f32_e32 v81, v81, v197
	v_add_f32_e32 v82, v82, v198
	v_add_f32_e32 v83, v83, v199
	v_add_f32_e32 v84, v84, v200
	v_add_f32_e32 v85, v85, v201
	v_add_f32_e32 v86, v86, v202
	v_add_f32_e32 v87, v87, v203
	v_add_f32_e32 v88, v88, v204
	v_add_f32_e32 v89, v89, v205
	v_add_f32_e32 v90, v90, v206
	v_add_f32_e32 v91, v91, v207
	v_add_f32_e32 v92, v92, v208
	v_add_f32_e32 v93, v93, v209
	v_add_f32_e32 v94, v94, v210
	v_add_f32_e32 v95, v95, v211
	s_waitcnt vmcnt(0)
	v_add_f32_e32 v96, v96, v212
	v_add_f32_e32 v97, v97, v213
	v_add_f32_e32 v98, v98, v214
	v_add_f32_e32 v99, v99, v215
	v_add_f32_e32 v100, v100, v216
	v_add_f32_e32 v101, v101, v217
	v_add_f32_e32 v102, v102, v218
	v_add_f32_e32 v103, v103, v219
	v_add_f32_e32 v104, v104, v220
	v_add_f32_e32 v105, v105, v221
	v_add_f32_e32 v106, v106, v222
	v_add_f32_e32 v107, v107, v223
	v_add_f32_e32 v108, v108, v224
	v_add_f32_e32 v109, v109, v225
	v_add_f32_e32 v110, v110, v226
	v_add_f32_e32 v111, v111, v227
	v_add_f32_e32 v112, v112, v228
	v_add_f32_e32 v113, v113, v229
	v_add_f32_e32 v114, v114, v230
	v_add_f32_e32 v115, v115, v231
	v_add_f32_e32 v116, v116, v232
	v_add_f32_e32 v117, v117, v233
	v_add_f32_e32 v118, v118, v234
	v_add_f32_e32 v119, v119, v235
	v_add_f32_e32 v120, v120, v236
	v_add_f32_e32 v121, v121, v237
	v_add_f32_e32 v122, v122, v238
	v_add_f32_e32 v123, v123, v239
	v_add_f32_e32 v124, v124, v240
	v_add_f32_e32 v125, v125, v241
	v_add_f32_e32 v126, v126, v242
	v_add_f32_e32 v127, v127, v243
	s_add_u32 s98, s98, 0x3f8000
	s_addc_u32 s99, s99, 0
	global_load_dwordx4 v[180:183], v160, s[98:99]
	s_add_u32 s98, s98, 0x400
	s_addc_u32 s99, s99, 0
	global_load_dwordx4 v[184:187], v160, s[98:99]
	s_add_u32 s98, s98, 0x400
	s_addc_u32 s99, s99, 0
	global_load_dwordx4 v[188:191], v160, s[98:99]
	s_add_u32 s98, s98, 0x400
	s_addc_u32 s99, s99, 0
	global_load_dwordx4 v[192:195], v160, s[98:99]
	s_add_u32 s98, s98, 0x400
	s_addc_u32 s99, s99, 0
	global_load_dwordx4 v[196:199], v160, s[98:99]
	s_add_u32 s98, s98, 0x400
	s_addc_u32 s99, s99, 0
	global_load_dwordx4 v[200:203], v160, s[98:99]
	s_add_u32 s98, s98, 0x400
	s_addc_u32 s99, s99, 0
	global_load_dwordx4 v[204:207], v160, s[98:99]
	s_add_u32 s98, s98, 0x400
	s_addc_u32 s99, s99, 0
	global_load_dwordx4 v[208:211], v160, s[98:99]
	s_add_u32 s98, s98, 0x400
	s_addc_u32 s99, s99, 0
	global_load_dwordx4 v[212:215], v160, s[98:99]
	s_add_u32 s98, s98, 0x400
	s_addc_u32 s99, s99, 0
	global_load_dwordx4 v[216:219], v160, s[98:99]
	s_add_u32 s98, s98, 0x400
	s_addc_u32 s99, s99, 0
	global_load_dwordx4 v[220:223], v160, s[98:99]
	s_add_u32 s98, s98, 0x400
	s_addc_u32 s99, s99, 0
	global_load_dwordx4 v[224:227], v160, s[98:99]
	s_add_u32 s98, s98, 0x400
	s_addc_u32 s99, s99, 0
	global_load_dwordx4 v[228:231], v160, s[98:99]
	s_add_u32 s98, s98, 0x400
	s_addc_u32 s99, s99, 0
	global_load_dwordx4 v[232:235], v160, s[98:99]
	s_add_u32 s98, s98, 0x400
	s_addc_u32 s99, s99, 0
	global_load_dwordx4 v[236:239], v160, s[98:99]
	s_add_u32 s98, s98, 0x400
	s_addc_u32 s99, s99, 0
	global_load_dwordx4 v[240:243], v160, s[98:99]
	s_add_u32 s98, s98, 0x400
	s_addc_u32 s99, s99, 0
	s_waitcnt vmcnt(8)
	v_add_f32_e32 v0, v0, v180
	v_add_f32_e32 v1, v1, v181
	v_add_f32_e32 v2, v2, v182
	v_add_f32_e32 v3, v3, v183
	v_add_f32_e32 v4, v4, v184
	v_add_f32_e32 v5, v5, v185
	v_add_f32_e32 v6, v6, v186
	v_add_f32_e32 v7, v7, v187
	v_add_f32_e32 v8, v8, v188
	v_add_f32_e32 v9, v9, v189
	v_add_f32_e32 v10, v10, v190
	v_add_f32_e32 v11, v11, v191
	v_add_f32_e32 v12, v12, v192
	v_add_f32_e32 v13, v13, v193
	v_add_f32_e32 v14, v14, v194
	v_add_f32_e32 v15, v15, v195
	v_add_f32_e32 v16, v16, v196
	v_add_f32_e32 v17, v17, v197
	v_add_f32_e32 v18, v18, v198
	v_add_f32_e32 v19, v19, v199
	v_add_f32_e32 v20, v20, v200
	v_add_f32_e32 v21, v21, v201
	v_add_f32_e32 v22, v22, v202
	v_add_f32_e32 v23, v23, v203
	v_add_f32_e32 v24, v24, v204
	v_add_f32_e32 v25, v25, v205
	v_add_f32_e32 v26, v26, v206
	v_add_f32_e32 v27, v27, v207
	v_add_f32_e32 v28, v28, v208
	v_add_f32_e32 v29, v29, v209
	v_add_f32_e32 v30, v30, v210
	v_add_f32_e32 v31, v31, v211
	global_load_dwordx4 v[180:183], v160, s[98:99]
	s_add_u32 s98, s98, 0x400
	s_addc_u32 s99, s99, 0
	global_load_dwordx4 v[184:187], v160, s[98:99]
	s_add_u32 s98, s98, 0x400
	s_addc_u32 s99, s99, 0
	global_load_dwordx4 v[188:191], v160, s[98:99]
	s_add_u32 s98, s98, 0x400
	s_addc_u32 s99, s99, 0
	global_load_dwordx4 v[192:195], v160, s[98:99]
	s_add_u32 s98, s98, 0x400
	s_addc_u32 s99, s99, 0
	global_load_dwordx4 v[196:199], v160, s[98:99]
	s_add_u32 s98, s98, 0x400
	s_addc_u32 s99, s99, 0
	global_load_dwordx4 v[200:203], v160, s[98:99]
	s_add_u32 s98, s98, 0x400
	s_addc_u32 s99, s99, 0
	global_load_dwordx4 v[204:207], v160, s[98:99]
	s_add_u32 s98, s98, 0x400
	s_addc_u32 s99, s99, 0
	global_load_dwordx4 v[208:211], v160, s[98:99]
	s_add_u32 s98, s98, 0x400
	s_addc_u32 s99, s99, 0
	s_waitcnt vmcnt(8)
; __device__ __forceinline__ u32x2 pk4(f32x4 v) { u32x2 w; w.x = cvt_pk_bf16(v[0], v[1]); w.y = cvt_pk_bf16(v[2], v[3]); return w; }
; __device__ __forceinline__ f32x4 up4(u32x2 w) { return (f32x4){bf_lo(w.x), bf_hi(w.x), bf_lo(w.y), bf_hi(w.y)}; }
; #define GEMM_N1024(EPI, Aoff, Woff, Mrows, Kdim, rowbase, Gn, cid, ...) do { pg8::Gemm g{(const bf16_t*)(a.ws + (Aoff)) + (size_t)(rowbase) * (Kdim), (const bf16_t*)(a.ws + (Woff)), (Mrows), 1024, (Kdim)}; \
;         pg8::StaticOrder S; S.init((Mrows), 1024, (Gn), (cid)); EPI E{__VA_ARGS__, (rowbase)}; pg8::gemm_phase<EPI, pg8::StaticOrder, false, true>(lds, g, S, E); } while (0)
;     __device__ __forceinline__ void operator()(const AccT& acc, const pg8::Unit& u, int wr, int wc, int fr, int fq) const {
;     ...
;             for (int m = 0; m < 4; ++m) { const int row = row0 + ai * 128 + m * 16; float ss = 0.f;
; #pragma unroll
;                 for (int bj = 0; bj < 2; ++bj)
; #pragma unroll
;                     for (int n = 0; n < 2; ++n) { f32x4 v = acc[ai][bj][m][n]; const size_t idx = (size_t)row * 1024 + col0 + bj * 128 + n * 16;
;                         if (MODE == 0) v = v * up4(*(const u32x2*)(io + idx));
;                         else if (MODE == 1) v = up4(*(const u32x2*)(io + idx)) + up4(*(const u32x2*)(g2 + idx)) * v;
;                         else ss += (v[0] * v[0] + v[1] * v[1]) + (v[2] * v[2] + v[3] * v[3]);
;                         if (!DRYE || v[0] == 123.456f) *(u32x2*)(io + idx) = pk4(v); }
;                 if (MODE == 2 && !DRYE) { ss += __shfl_xor(ss, 16); ss += __shfl_xor(ss, 32); if (fq == 0) atomicAdd(rowss + row, ss); } }
; __global__ void __launch_bounds__(512) fwd_kernel(Args a) {
;     ...
;         if (G >= 32 && bx < 16) GEMM_N1024(EpiN1024<2>, A_HID, WS_WDN, MS, DFF, MP, 16, bx, (bf16_t*)(a.ws + A_GA), nullptr, (float*)(a.ws + WS_RSS2));
	v_add_f32_e32 v32, v32, v212
	v_add_f32_e32 v33, v33, v213
	v_add_f32_e32 v34, v34, v214
	v_add_f32_e32 v35, v35, v215
	v_add_f32_e32 v36, v36, v216
	v_add_f32_e32 v37, v37, v217
	v_add_f32_e32 v38, v38, v218
	v_add_f32_e32 v39, v39, v219
	v_add_f32_e32 v40, v40, v220
	v_add_f32_e32 v41, v41, v221
	v_add_f32_e32 v42, v42, v222
	v_add_f32_e32 v43, v43, v223
	v_add_f32_e32 v44, v44, v224
	v_add_f32_e32 v45, v45, v225
	v_add_f32_e32 v46, v46, v226
	v_add_f32_e32 v47, v47, v227
	v_add_f32_e32 v48, v48, v228
	v_add_f32_e32 v49, v49, v229
	v_add_f32_e32 v50, v50, v230
	v_add_f32_e32 v51, v51, v231
	v_add_f32_e32 v52, v52, v232
	v_add_f32_e32 v53, v53, v233
	v_add_f32_e32 v54, v54, v234
	v_add_f32_e32 v55, v55, v235
	v_add_f32_e32 v56, v56, v236
	v_add_f32_e32 v57, v57, v237
	v_add_f32_e32 v58, v58, v238
	v_add_f32_e32 v59, v59, v239
	v_add_f32_e32 v60, v60, v240
	v_add_f32_e32 v61, v61, v241
	v_add_f32_e32 v62, v62, v242
	v_add_f32_e32 v63, v63, v243
	global_load_dwordx4 v[212:215], v160, s[98:99]
	s_add_u32 s98, s98, 0x400
	s_addc_u32 s99, s99, 0
	global_load_dwordx4 v[216:219], v160, s[98:99]
	s_add_u32 s98, s98, 0x400
	s_addc_u32 s99, s99, 0
	global_load_dwordx4 v[220:223], v160, s[98:99]
	s_add_u32 s98, s98, 0x400
	s_addc_u32 s99, s99, 0
	global_load_dwordx4 v[224:227], v160, s[98:99]
	s_add_u32 s98, s98, 0x400
	s_addc_u32 s99, s99, 0
	global_load_dwordx4 v[228:231], v160, s[98:99]
	s_add_u32 s98, s98, 0x400
	s_addc_u32 s99, s99, 0
	global_load_dwordx4 v[232:235], v160, s[98:99]
	s_add_u32 s98, s98, 0x400
	s_addc_u32 s99, s99, 0
	global_load_dwordx4 v[236:239], v160, s[98:99]
	s_add_u32 s98, s98, 0x400
	s_addc_u32 s99, s99, 0
	global_load_dwordx4 v[240:243], v160, s[98:99]
	s_add_u32 s98, s98, 0x400
	s_addc_u32 s99, s99, 0
	s_waitcnt vmcnt(8)
	v_add_f32_e32 v64, v64, v180
	v_add_f32_e32 v65, v65, v181
	v_add_f32_e32 v66, v66, v182
	v_add_f32_e32 v67, v67, v183
	v_add_f32_e32 v68, v68, v184
	v_add_f32_e32 v69, v69, v185
	v_add_f32_e32 v70, v70, v186
	v_add_f32_e32 v71, v71, v187
	v_add_f32_e32 v72, v72, v188
	v_add_f32_e32 v73, v73, v189
	v_add_f32_e32 v74, v74, v190
	v_add_f32_e32 v75, v75, v191
	v_add_f32_e32 v76, v76, v192
	v_add_f32_e32 v77, v77, v193
	v_add_f32_e32 v78, v78, v194
	v_add_f32_e32 v79, v79, v195
	v_add_f32_e32 v80, v80, v196
	v_add_f32_e32 v81, v81, v197
	v_add_f32_e32 v82, v82, v198
	v_add_f32_e32 v83, v83, v199
	v_add_f32_e32 v84, v84, v200
	v_add_f32_e32 v85, v85, v201
	v_add_f32_e32 v86, v86, v202
	v_add_f32_e32 v87, v87, v203
	v_add_f32_e32 v88, v88, v204
	v_add_f32_e32 v89, v89, v205
	v_add_f32_e32 v90, v90, v206
	v_add_f32_e32 v91, v91, v207
	v_add_f32_e32 v92, v92, v208
	v_add_f32_e32 v93, v93, v209
	v_add_f32_e32 v94, v94, v210
	v_add_f32_e32 v95, v95, v211
	s_waitcnt vmcnt(0)
	v_add_f32_e32 v96, v96, v212
	v_add_f32_e32 v97, v97, v213
	v_add_f32_e32 v98, v98, v214
	v_add_f32_e32 v99, v99, v215
	v_add_f32_e32 v100, v100, v216
	v_add_f32_e32 v101, v101, v217
	v_add_f32_e32 v102, v102, v218
	v_add_f32_e32 v103, v103, v219
	v_add_f32_e32 v104, v104, v220
	v_add_f32_e32 v105, v105, v221
	v_add_f32_e32 v106, v106, v222
	v_add_f32_e32 v107, v107, v223
	v_add_f32_e32 v108, v108, v224
	v_add_f32_e32 v109, v109, v225
	v_add_f32_e32 v110, v110, v226
	v_add_f32_e32 v111, v111, v227
	v_add_f32_e32 v112, v112, v228
	v_add_f32_e32 v113, v113, v229
	v_add_f32_e32 v114, v114, v230
	v_add_f32_e32 v115, v115, v231
	v_add_f32_e32 v116, v116, v232
	v_add_f32_e32 v117, v117, v233
	v_add_f32_e32 v118, v118, v234
	v_add_f32_e32 v119, v119, v235
	v_add_f32_e32 v120, v120, v236
	v_add_f32_e32 v121, v121, v237
	v_add_f32_e32 v122, v122, v238
	v_add_f32_e32 v123, v123, v239
	v_add_f32_e32 v124, v124, v240
	v_add_f32_e32 v125, v125, v241
	v_add_f32_e32 v126, v126, v242
	v_add_f32_e32 v127, v127, v243
	v_and_b32_e32 v147, 64, v146
	v_xor_b32_e32 v139, 16, v146
	v_add_u32_e32 v147, 64, v147
	v_cmp_lt_i32_e32 vcc, v139, v147
	v_lshl_add_u32 v149, s47, 8, v140
	v_add_u32_e32 v138, 0x4000, v149
	v_cndmask_b32_e32 v139, v146, v139, vcc
	v_lshlrev_b32_e32 v148, 2, v139
	v_xor_b32_e32 v139, 32, v146
	v_cmp_lt_i32_e32 vcc, v139, v147
	v_lshl_or_b32 v136, s48, 8, v142
	v_mul_f32_e32 v152, v125, v125
	v_cndmask_b32_e32 v139, v146, v139, vcc
	v_lshlrev_b32_e32 v147, 2, v139
	v_ashrrev_i32_e32 v139, 31, v138
	v_lshlrev_b64 v[150:151], 11, v[138:139]
	v_mul_f32_e32 v153, v127, v127
	v_ashrrev_i32_e32 v137, 31, v136
	v_fmac_f32_e32 v152, v124, v124
	v_fmac_f32_e32 v153, v126, v126
	v_cvt_pk_bf16_f32 v124, v124, v125
	v_cvt_pk_bf16_f32 v125, v126, v127
	v_lshl_add_u64 v[126:127], s[10:11], 0, v[150:151]
	v_lshl_add_u64 v[126:127], v[136:137], 1, v[126:127]
	global_store_dwordx2 v[126:127], v[124:125], off
	v_mul_f32_e32 v124, v121, v121
	v_mul_f32_e32 v125, v123, v123
	v_fmac_f32_e32 v124, v120, v120
	v_fmac_f32_e32 v125, v122, v122
	v_add_f32_e32 v124, v124, v125
	v_cvt_pk_bf16_f32 v120, v120, v121
	v_mul_f32_e32 v121, v117, v117
	v_mul_f32_e32 v125, v119, v119
	v_add_f32_e32 v152, v152, v153
	v_fmac_f32_e32 v121, v116, v116
	v_fmac_f32_e32 v125, v118, v118
	v_add_f32_e32 v124, v152, v124
	v_add_f32_e32 v121, v121, v125
	v_add_f32_e32 v121, v124, v121
	v_mul_f32_e32 v124, v109, v109
	v_mul_f32_e32 v125, v111, v111
	v_fmac_f32_e32 v124, v108, v108
	v_fmac_f32_e32 v125, v110, v110
	v_add_f32_e32 v124, v124, v125
	v_add_f32_e32 v124, v121, v124
	ds_bpermute_b32 v125, v148, v124
	v_cvt_pk_bf16_f32 v121, v122, v123
	global_store_dwordx2 v[126:127], v[120:121], off offset:32
	v_cvt_pk_bf16_f32 v120, v116, v117
	v_cvt_pk_bf16_f32 v121, v118, v119
	s_waitcnt lgkmcnt(0)
	v_add_f32_e32 v116, v124, v125
	ds_bpermute_b32 v117, v147, v116
	v_cvt_pk_bf16_f32 v108, v108, v109
	v_cvt_pk_bf16_f32 v109, v110, v111
	global_store_dwordx2 v[126:127], v[120:121], off offset:256
	global_store_dwordx2 v[126:127], v[108:109], off offset:288
	s_and_saveexec_b64 s[22:23], s[0:1]
	s_cbranch_execz .LBB0_1443
	v_lshl_add_u64 v[108:109], v[138:139], 2, s[14:15]
	s_waitcnt lgkmcnt(0)
	v_add_f32_e32 v110, v116, v117
	global_atomic_add_f32 v[108:109], v110, off
